# phase_h rewritten by hand like phase_mid: wave-per-row, g hoisted, all loads of the next row in flight (counted vmcnt), on top of the batched projection epilogue
# speedup vs baseline: 1.0012x; 1.0012x over previous
; DI int otid() { int t = threadIdx.x; asm volatile("" : "+v"(t)); return t; }
; DI int obid() { int b = blockIdx.x; asm volatile("" : "+s"(b)); return b; }
; DI int ogrid() { int g = gridDim.x; asm volatile("" : "+s"(g)); return g; }
; DI void store_bf4(bf16_t* p, f32x4 v) { u32x2 w; w.x = pk2(v[0], v[1]); w.y = pk2(v[2], v[3]); *(u32x2*)p = w; }
; DI void phase_h(KP P) {
;     const int tid_ = otid(), lane = tid_ & 63, gw = obid() * 8 + (tid_ >> 6), nw = ogrid() * 8;
;     for (int row = gw; row < MT; row += nw) {
;         const float* xr = row < MP ? P->x_p + (long)row * DM : P->x_s + (long)(row - MP) * DM;
;         const float* ad = P->ada + ada_b(row) * 6144;
;         f32x4 v[4]; float s = 0.f;
; #pragma unroll
;         for (int i = 0; i < 4; ++i) { v[i] = *(const f32x4*)(xr + i * 256 + lane * 4); s += v[i][0] * v[i][0] + v[i][1] * v[i][1] + v[i][2] * v[i][2] + v[i][3] * v[i][3]; }
; #pragma unroll
;         for (int o = 1; o < 64; o <<= 1) s += __shfl_xor(s, o);
;         const float rstd = rsqrtf(s * (1.0f / DM) + EPS);
; #pragma unroll
;         for (int i = 0; i < 4; ++i) { const int c = i * 256 + lane * 4;
;             const f32x4 g = *(const f32x4*)(P->g_pre_mix + c), sh = *(const f32x4*)(ad + c), scl = *(const f32x4*)(ad + 1024 + c);
;             store_bf4(P->h + (long)row * DM + c, v[i] * rstd * g * (1.0f + scl) + sh); }
.LBB0_226:
	v_readlane_b32 s4, v251, 1
	s_cmp_lt_i32 s4, 2
	s_cselect_b64 s[6:7], -1, 0
	s_and_b64 s[2:3], s[6:7], s[2:3]
	s_andn2_b64 vcc, exec, s[2:3]
	s_cbranch_vccnz .LBB0_235
	s_mov_b64 s[2:3], s[0:1]
	s_load_dwordx4 s[12:15], s[2:3], 0x0
	s_load_dwordx2 s[10:11], s[2:3], 0xe8
	s_load_dwordx2 s[16:17], s[2:3], 0x58
	s_load_dwordx2 s[18:19], s[2:3], 0x100
	v_lshrrev_b32_e32 v4, 6, v186
	v_and_b32_e32 v1, 63, v186
	s_lshl_b32 s4, s54, 3
	s_lshl_b32 s5, s55, 3
	v_readfirstlane_b32 s20, v4
	v_lshlrev_b32_e32 v0, 4, v1
	v_lshlrev_b32_e32 v2, 3, v1
	v_xor_b32_e32 v3, 16, v1
	v_lshlrev_b32_e32 v6, 2, v3
	v_xor_b32_e32 v3, 32, v1
	v_lshlrev_b32_e32 v7, 2, v3
	s_add_i32 s4, s4, s20
	s_cmpk_ge_i32 s4, 0x4100
	s_cbranch_scc1 .Lph_done
	s_waitcnt lgkmcnt(0)
	global_load_dwordx4 v[8:11], v0, s[16:17]
	global_load_dwordx4 v[12:15], v0, s[16:17] offset:1024
	global_load_dwordx4 v[16:19], v0, s[16:17] offset:2048
	global_load_dwordx4 v[20:23], v0, s[16:17] offset:3072
	s_add_i32 s24, s4, 0xffffc000
	s_lshr_b32 s26, s4, 13
	s_lshr_b32 s27, s24, 5
	s_add_i32 s27, s27, 2
	s_cmp_lt_i32 s4, 0x4000
	s_cselect_b32 s22, s12, s14
	s_cselect_b32 s23, s13, s15
	s_cselect_b32 s25, s4, s24
	s_cselect_b32 s26, s26, s27
	s_lshl_b32 s25, s25, 12
	s_add_u32 s22, s22, s25
	s_addc_u32 s23, s23, 0
	s_mul_i32 s26, s26, 0x6000
	s_add_u32 s24, s10, s26
	s_addc_u32 s25, s11, 0
	s_add_u32 s26, s24, 0x1000
	s_addc_u32 s27, s25, 0
	global_load_dwordx4 v[72:75], v0, s[22:23]
	global_load_dwordx4 v[76:79], v0, s[22:23] offset:1024
	global_load_dwordx4 v[80:83], v0, s[22:23] offset:2048
	global_load_dwordx4 v[84:87], v0, s[22:23] offset:3072
	global_load_dwordx4 v[88:91], v0, s[24:25]
	global_load_dwordx4 v[92:95], v0, s[24:25] offset:1024
	global_load_dwordx4 v[96:99], v0, s[24:25] offset:2048
	global_load_dwordx4 v[100:103], v0, s[24:25] offset:3072
	global_load_dwordx4 v[104:107], v0, s[26:27]
	global_load_dwordx4 v[108:111], v0, s[26:27] offset:1024
	global_load_dwordx4 v[112:115], v0, s[26:27] offset:2048
	global_load_dwordx4 v[116:119], v0, s[26:27] offset:3072
	s_waitcnt vmcnt(0)
	s_branch .Lph_body

; DI void store_bf4(bf16_t* p, f32x4 v) { u32x2 w; w.x = pk2(v[0], v[1]); w.y = pk2(v[2], v[3]); *(u32x2*)p = w; }
; DI void phase_h(KP P) {
;     ...
;     for (int row = gw; row < MT; row += nw) {
;         const float* xr = row < MP ? P->x_p + (long)row * DM : P->x_s + (long)(row - MP) * DM;
;         const float* ad = P->ada + ada_b(row) * 6144;
;         f32x4 v[4]; float s = 0.f;
; #pragma unroll
;         for (int i = 0; i < 4; ++i) { v[i] = *(const f32x4*)(xr + i * 256 + lane * 4); s += v[i][0] * v[i][0] + v[i][1] * v[i][1] + v[i][2] * v[i][2] + v[i][3] * v[i][3]; }
; #pragma unroll
;         for (int o = 1; o < 64; o <<= 1) s += __shfl_xor(s, o);
;         const float rstd = rsqrtf(s * (1.0f / DM) + EPS);
; #pragma unroll
;         for (int i = 0; i < 4; ++i) { const int c = i * 256 + lane * 4;
;             const f32x4 g = *(const f32x4*)(P->g_pre_mix + c), sh = *(const f32x4*)(ad + c), scl = *(const f32x4*)(ad + 1024 + c);
;             store_bf4(P->h + (long)row * DM + c, v[i] * rstd * g * (1.0f + scl) + sh); }
;     }
.Lph_body:
	v_mov_b64_e32 v[24:25], v[72:73]
	v_mov_b64_e32 v[26:27], v[74:75]
	v_mov_b64_e32 v[28:29], v[76:77]
	v_mov_b64_e32 v[30:31], v[78:79]
	v_mov_b64_e32 v[32:33], v[80:81]
	v_mov_b64_e32 v[34:35], v[82:83]
	v_mov_b64_e32 v[36:37], v[84:85]
	v_mov_b64_e32 v[38:39], v[86:87]
	v_mov_b64_e32 v[40:41], v[88:89]
	v_mov_b64_e32 v[42:43], v[90:91]
	v_mov_b64_e32 v[44:45], v[92:93]
	v_mov_b64_e32 v[46:47], v[94:95]
	v_mov_b64_e32 v[48:49], v[96:97]
	v_mov_b64_e32 v[50:51], v[98:99]
	v_mov_b64_e32 v[52:53], v[100:101]
	v_mov_b64_e32 v[54:55], v[102:103]
	v_mov_b64_e32 v[56:57], v[104:105]
	v_mov_b64_e32 v[58:59], v[106:107]
	v_mov_b64_e32 v[60:61], v[108:109]
	v_mov_b64_e32 v[62:63], v[110:111]
	v_mov_b64_e32 v[64:65], v[112:113]
	v_mov_b64_e32 v[66:67], v[114:115]
	v_mov_b64_e32 v[68:69], v[116:117]
	v_mov_b64_e32 v[70:71], v[118:119]
	s_add_i32 s21, s4, s5
	s_cmpk_ge_i32 s21, 0x4100
	s_cbranch_scc1 .Lph_nonext
	s_add_i32 s24, s21, 0xffffc000
	s_lshr_b32 s26, s21, 13
	s_lshr_b32 s27, s24, 5
	s_add_i32 s27, s27, 2
	s_cmp_lt_i32 s21, 0x4000
	s_cselect_b32 s22, s12, s14
	s_cselect_b32 s23, s13, s15
	s_cselect_b32 s25, s21, s24
	s_cselect_b32 s26, s26, s27
	s_lshl_b32 s25, s25, 12
	s_add_u32 s22, s22, s25
	s_addc_u32 s23, s23, 0
	s_mul_i32 s26, s26, 0x6000
	s_add_u32 s24, s10, s26
	s_addc_u32 s25, s11, 0
	s_add_u32 s26, s24, 0x1000
	s_addc_u32 s27, s25, 0
	global_load_dwordx4 v[72:75], v0, s[22:23]
	global_load_dwordx4 v[76:79], v0, s[22:23] offset:1024
	global_load_dwordx4 v[80:83], v0, s[22:23] offset:2048
	global_load_dwordx4 v[84:87], v0, s[22:23] offset:3072
	global_load_dwordx4 v[88:91], v0, s[24:25]
	global_load_dwordx4 v[92:95], v0, s[24:25] offset:1024
	global_load_dwordx4 v[96:99], v0, s[24:25] offset:2048
	global_load_dwordx4 v[100:103], v0, s[24:25] offset:3072
	global_load_dwordx4 v[104:107], v0, s[26:27]
	global_load_dwordx4 v[108:111], v0, s[26:27] offset:1024
	global_load_dwordx4 v[112:115], v0, s[26:27] offset:2048
	global_load_dwordx4 v[116:119], v0, s[26:27] offset:3072
.Lph_nonext:
	v_mul_f32_e32 v120, v24, v24
	v_mul_f32_e32 v121, v25, v25
	v_fmac_f32_e32 v120, v26, v26
	v_fmac_f32_e32 v121, v27, v27
	v_fmac_f32_e32 v120, v28, v28
	v_fmac_f32_e32 v121, v29, v29
	v_fmac_f32_e32 v120, v30, v30
	v_fmac_f32_e32 v121, v31, v31
	v_fmac_f32_e32 v120, v32, v32
	v_fmac_f32_e32 v121, v33, v33
	v_fmac_f32_e32 v120, v34, v34
	v_fmac_f32_e32 v121, v35, v35
	v_fmac_f32_e32 v120, v36, v36
	v_fmac_f32_e32 v121, v37, v37
	v_fmac_f32_e32 v120, v38, v38
	v_fmac_f32_e32 v121, v39, v39
	v_add_f32_e32 v120, v120, v121
	s_nop 1
	v_mov_b32_dpp v121, v120 quad_perm:[1,0,3,2] row_mask:0xf bank_mask:0xf bound_ctrl:1
	v_add_f32_e32 v120, v120, v121
	s_nop 1
	v_mov_b32_dpp v121, v120 quad_perm:[2,3,0,1] row_mask:0xf bank_mask:0xf bound_ctrl:1
	v_add_f32_e32 v120, v120, v121
	s_nop 1
	v_mov_b32_dpp v121, v120 row_ror:4 row_mask:0xf bank_mask:0xf bound_ctrl:1
	v_add_f32_e32 v120, v120, v121
	s_nop 1
	v_mov_b32_dpp v121, v120 row_ror:8 row_mask:0xf bank_mask:0xf bound_ctrl:1
	v_add_f32_e32 v120, v120, v121
	ds_bpermute_b32 v121, v6, v120
	s_lshl_b32 s26, s4, 11
	s_add_u32 s16, s18, s26
	s_addc_u32 s17, s19, 0
	v_mov_b32_e32 v122, 0x358637bd
	s_waitcnt lgkmcnt(0)
	v_add_f32_e32 v120, v120, v121
	ds_bpermute_b32 v121, v7, v120
	s_waitcnt lgkmcnt(0)
	v_add_f32_e32 v120, v120, v121
	v_fmamk_f32 v120, v120, 0x3a800000, v122
	v_rsq_f32_e32 v120, v120
	s_nop 0
	v_pk_mul_f32 v[124:125], v[24:25], v[120:121] op_sel_hi:[1,0]
	v_pk_mul_f32 v[126:127], v[26:27], v[120:121] op_sel_hi:[1,0]
	v_pk_add_f32 v[128:129], v[56:57], 1.0 op_sel_hi:[1,0]
	v_pk_add_f32 v[130:131], v[58:59], 1.0 op_sel_hi:[1,0]
	v_pk_mul_f32 v[124:125], v[8:9], v[124:125]
	v_pk_mul_f32 v[126:127], v[10:11], v[126:127]
	v_pk_fma_f32 v[124:125], v[128:129], v[124:125], v[40:41]
	v_pk_fma_f32 v[126:127], v[130:131], v[126:127], v[42:43]
	v_cvt_pk_bf16_f32 v124, v124, v125
	v_cvt_pk_bf16_f32 v125, v126, v127
	global_store_dwordx2 v2, v[124:125], s[16:17]
	v_pk_mul_f32 v[132:133], v[28:29], v[120:121] op_sel_hi:[1,0]
	v_pk_mul_f32 v[134:135], v[30:31], v[120:121] op_sel_hi:[1,0]
	v_pk_add_f32 v[136:137], v[60:61], 1.0 op_sel_hi:[1,0]
	v_pk_add_f32 v[138:139], v[62:63], 1.0 op_sel_hi:[1,0]
	v_pk_mul_f32 v[132:133], v[12:13], v[132:133]
	v_pk_mul_f32 v[134:135], v[14:15], v[134:135]
	v_pk_fma_f32 v[132:133], v[136:137], v[132:133], v[44:45]
	v_pk_fma_f32 v[134:135], v[138:139], v[134:135], v[46:47]
	v_cvt_pk_bf16_f32 v132, v132, v133
	v_cvt_pk_bf16_f32 v133, v134, v135
	global_store_dwordx2 v2, v[132:133], s[16:17] offset:512
	v_pk_mul_f32 v[140:141], v[32:33], v[120:121] op_sel_hi:[1,0]
	v_pk_mul_f32 v[142:143], v[34:35], v[120:121] op_sel_hi:[1,0]
	v_pk_add_f32 v[144:145], v[64:65], 1.0 op_sel_hi:[1,0]
	v_pk_add_f32 v[146:147], v[66:67], 1.0 op_sel_hi:[1,0]
	v_pk_mul_f32 v[140:141], v[16:17], v[140:141]
	v_pk_mul_f32 v[142:143], v[18:19], v[142:143]
	v_pk_fma_f32 v[140:141], v[144:145], v[140:141], v[48:49]
	v_pk_fma_f32 v[142:143], v[146:147], v[142:143], v[50:51]
	v_cvt_pk_bf16_f32 v140, v140, v141
	v_cvt_pk_bf16_f32 v141, v142, v143
	global_store_dwordx2 v2, v[140:141], s[16:17] offset:1024
	v_pk_mul_f32 v[148:149], v[36:37], v[120:121] op_sel_hi:[1,0]
	v_pk_mul_f32 v[150:151], v[38:39], v[120:121] op_sel_hi:[1,0]
	v_pk_add_f32 v[152:153], v[68:69], 1.0 op_sel_hi:[1,0]
	v_pk_add_f32 v[154:155], v[70:71], 1.0 op_sel_hi:[1,0]
	v_pk_mul_f32 v[148:149], v[20:21], v[148:149]
	v_pk_mul_f32 v[150:151], v[22:23], v[150:151]
	v_pk_fma_f32 v[148:149], v[152:153], v[148:149], v[52:53]
	v_pk_fma_f32 v[150:151], v[154:155], v[150:151], v[54:55]
	v_cvt_pk_bf16_f32 v148, v148, v149
	v_cvt_pk_bf16_f32 v149, v150, v151
	global_store_dwordx2 v2, v[148:149], s[16:17] offset:1536
	s_mov_b32 s4, s21
	s_cmpk_lt_i32 s4, 0x4100
	s_cbranch_scc1 .Lph_loop
.Lph_done:
	s_mov_b64 s[8:9], exec
.LBB0_234:
	s_or_b64 exec, exec, s[8:9]
